# P0: cooperative-groups grid.sync replaced by a single-counter grid barrier in the zeroed control area
# baseline (speedup 1.0000x reference)
; __global__ void __launch_bounds__(NTHR, 2) fwd_kernel(Params p) {
;     ...
;   grid.sync();
.LBB0_33:
	v_lshrrev_b32_e32 v2, 20, v0
	v_lshrrev_b32_e32 v0, 10, v0
	v_or_b32_e32 v0, v0, v2
	s_movk_i32 s1, 0x3ff
	v_and_or_b32 v0, v0, s1, v1
	v_cmp_eq_u32_e32 vcc, 0, v0
	s_waitcnt vmcnt(0)
	s_barrier
	s_and_saveexec_b64 s[2:3], vcc
	s_cbranch_execz .LBB0_43
	buffer_wbl2 sc1
	s_waitcnt vmcnt(0)
	s_add_u32 s4, s42, 0x8000
	s_addc_u32 s5, s43, 0
	v_mov_b32_e32 v2, 0
	v_mov_b32_e32 v0, 1
	global_atomic_add v2, v0, s[4:5]
.Lp0_spin:
	s_sleep 1
	global_load_dword v0, v2, s[4:5] sc1
	s_waitcnt vmcnt(0)
	v_cmp_gt_u32_e32 vcc, 0x100, v0
	s_cbranch_vccnz .Lp0_spin
	buffer_inv sc1
